# per-segment priority: s_setprio 1 during the QK segment, 0 for softmax/PV, in both attention loops; on top of serial-chain + loop-edge + pipelined mem-attention reads
# baseline (speedup 1.0000x reference)
; #define SBAR() __builtin_amdgcn_sched_barrier(0)
; #define QK_WAIT(N) do { asm volatile("s_waitcnt lgkmcnt(" #N ")" ::: "memory"); SBAR(); } while (0)
; __device__ __forceinline__ float qkt_deep(f32x16& p0, f32x16& p1, const int (&ka)[4], const bf16x8 (&qr)[8]) {
;     ...
;   QD_RD0(0); QD_RD0(1); QD_RD0(2); QD_RD0(3); QD_RD0(4); QD_RD0(5); QD_RD0(6); QD_RD0(7);
;   QK_WAIT(7); QD_MM0(0); SBAR(); QD_RD1(0);
;   QK_WAIT(7); QD_MM0(1); SBAR(); QD_RD1(1);
;   QK_WAIT(7); QD_MM0(2); SBAR(); QD_RD1(2);
;   QK_WAIT(7); QD_MM0(3); SBAR(); QD_RD1(3);
;   QK_WAIT(7); QD_MM0(4); SBAR(); QD_RD1(4);
;   QK_WAIT(7); QD_MM0(5); SBAR(); QD_RD1(5);
;   QK_WAIT(7); QD_MM0(6); SBAR(); QD_RD1(6);
;   QK_WAIT(7); QD_MM0(7); SBAR(); QD_RD1(7);
;   QK_WAIT(7); QD_MM1(0); pm = fmaxf(p0[0], p0[1]); SBAR();
;   QK_WAIT(6); QD_MM1(1); pm = fmaxf(fmaxf(pm, p0[2]), p0[3]); SBAR();
;   QK_WAIT(5); QD_MM1(2); pm = fmaxf(fmaxf(pm, p0[4]), p0[5]); SBAR();
;   QK_WAIT(4); QD_MM1(3); pm = fmaxf(fmaxf(pm, p0[6]), p0[7]); SBAR();
;   QK_WAIT(3); QD_MM1(4); pm = fmaxf(fmaxf(pm, p0[8]), p0[9]); SBAR();
;   QK_WAIT(2); QD_MM1(5); pm = fmaxf(fmaxf(pm, p0[10]), p0[11]); SBAR();
;   QK_WAIT(1); QD_MM1(6); pm = fmaxf(fmaxf(pm, p0[12]), p0[13]); SBAR();
;   QK_WAIT(0); QD_MM1(7); pm = fmaxf(fmaxf(pm, p0[14]), p0[15]);
;   return pm;
; }
; template <int LD>
; __device__ __forceinline__ void attn256_body(const bf16_t* __restrict__ Qb, const bf16_t* __restrict__ Kh, const unsigned char* __restrict__ Vimg, int seq, char* lds, LAS unsigned char* ldsl,
;                                              f32x16 (&o)[8], float (&rli)[16]) {
;     ...
;   for (int j = 0; j < NT; ++j) {
;     const int cur = j & 1;
;     if (j + 1 < NT) { if (cur) A2_DMA(0, (j + 1) * 64); else A2_DMA(1, (j + 1) * 64); }
;     f32x16 p0 = f32x16{}, p1 = f32x16{}; float pmax;
;     { int ka[4];
; #pragma unroll
;       for (int q = 0; q < 4; ++q) ka[q] = kbase + cur * A2_STAGE + (((2 * q + hi) ^ (r32 & 7)) << 4);
;       pmax = qkt_deep(p0, p1, ka, qr); }
; #pragma unroll
;     for (int r = 0; r < 16; ++r) pmax = fmaxf(pmax, p1[r]);
;     pmax = half_swap_max(pmax);
;     float mn, alpha;
;     if (__builtin_expect(__all(pmax - m_reg <= ATT_THR / ATT_SCALE), 1)) { mn = m_reg; alpha = 1.f; }
;     else { mn = fmaxf(m_reg, pmax); alpha = __builtin_amdgcn_exp2f((m_reg - mn) * C); m_reg = mn; }
;     const float mnC = -mn * C; float ps;
.LBB0_663:
	s_setprio 1
	s_mul_i32 s4, s4, 0xc000
	s_waitcnt lgkmcnt(0)
	v_add_u32_e32 v0, s4, v221
	v_add_u32_e32 v14, v0, v233
	v_add_u32_e32 v15, v0, v234
	v_add_u32_e32 v252, v0, v235
	v_add_u32_e32 v0, v0, v236
	ds_read_b128 v[2:5], v14 offset:0
	ds_read_b128 v[6:9], v15 offset:0
	ds_read_b128 v[10:13], v252 offset:0
	ds_read_b128 v[144:147], v0 offset:0
	ds_read_b128 v[148:151], v14 offset:0x80
	ds_read_b128 v[152:155], v15 offset:0x80
	ds_read_b128 v[156:159], v252 offset:0x80
	ds_read_b128 v[208:211], v0 offset:0x80
	s_waitcnt lgkmcnt(7)
	s_nop 0
	v_mfma_f32_32x32x16_bf16 v[160:175], v[2:5], v[176:179], 0
	ds_read_b128 v[2:5], v14 offset:0x2000
	s_waitcnt lgkmcnt(7)
	s_nop 0
	v_mfma_f32_32x32x16_bf16 v[160:175], v[6:9], v[180:183], v[160:175]
	ds_read_b128 v[6:9], v15 offset:0x2000
	s_waitcnt lgkmcnt(7)
	s_nop 0
	v_mfma_f32_32x32x16_bf16 v[160:175], v[10:13], v[184:187], v[160:175]
	ds_read_b128 v[10:13], v252 offset:0x2000
	s_waitcnt lgkmcnt(7)
	s_nop 0
	v_mfma_f32_32x32x16_bf16 v[160:175], v[144:147], v[188:191], v[160:175]
	ds_read_b128 v[240:243], v0 offset:0x2000
	s_waitcnt lgkmcnt(7)
	s_nop 0
	v_mfma_f32_32x32x16_bf16 v[160:175], v[148:151], v[192:195], v[160:175]
	ds_read_b128 v[244:247], v14 offset:0x2080
	s_waitcnt lgkmcnt(7)
	s_nop 0
	v_mfma_f32_32x32x16_bf16 v[160:175], v[152:155], v[196:199], v[160:175]
	ds_read_b128 v[248:251], v15 offset:0x2080
	s_waitcnt lgkmcnt(7)
	s_nop 0
	v_mfma_f32_32x32x16_bf16 v[160:175], v[156:159], v[200:203], v[160:175]
	ds_read_b128 v[212:215], v252 offset:0x2080
	s_waitcnt lgkmcnt(7)
	s_nop 0
	v_mfma_f32_32x32x16_bf16 v[160:175], v[208:211], v[204:207], v[160:175]
	ds_read_b128 v[208:211], v0 offset:0x2080
	s_waitcnt lgkmcnt(7)
	v_mfma_f32_32x32x16_bf16 v[144:159], v[2:5], v[176:179], 0
	s_nop 10
	v_max_f32_e32 v0, v161, v161
	v_max_f32_e32 v2, v160, v160
	v_max_f32_e32 v0, v2, v0
	s_waitcnt lgkmcnt(6)
	s_nop 0
	v_mfma_f32_32x32x16_bf16 v[144:159], v[6:9], v[180:183], v[144:159]
	v_max3_f32 v0, v0, v162, v163
	s_waitcnt lgkmcnt(5)
	s_nop 0
	v_mfma_f32_32x32x16_bf16 v[144:159], v[10:13], v[184:187], v[144:159]
	v_max3_f32 v0, v0, v164, v165
	s_waitcnt lgkmcnt(4)
	s_nop 0
	v_mfma_f32_32x32x16_bf16 v[144:159], v[240:243], v[188:191], v[144:159]
	v_max3_f32 v0, v0, v166, v167
	s_waitcnt lgkmcnt(3)
	s_nop 0
	v_mfma_f32_32x32x16_bf16 v[144:159], v[244:247], v[192:195], v[144:159]
	v_max3_f32 v0, v0, v168, v169
	s_waitcnt lgkmcnt(2)
	s_nop 0
	v_mfma_f32_32x32x16_bf16 v[144:159], v[248:251], v[196:199], v[144:159]
	v_max3_f32 v0, v0, v170, v171
	s_waitcnt lgkmcnt(1)
	s_nop 0
	v_mfma_f32_32x32x16_bf16 v[144:159], v[212:215], v[200:203], v[144:159]
	v_max3_f32 v0, v0, v172, v173
	s_waitcnt lgkmcnt(0)
	s_nop 0
	v_mfma_f32_32x32x16_bf16 v[144:159], v[208:211], v[204:207], v[144:159]
	s_setprio 0
	v_max3_f32 v0, v0, v174, v175
	v_mul_f32_e32 v14, 0xbe0293ee, v238
	s_nop 9
	v_max3_f32 v2, v144, v145, v146
	v_max3_f32 v3, v147, v148, v149
	v_max3_f32 v4, v150, v151, v152
	v_max3_f32 v5, v153, v154, v155
	v_max3_f32 v6, v156, v157, v158
	v_max3_f32 v2, v2, v3, v4
	v_max3_f32 v5, v5, v6, v159
	v_max3_f32 v0, v0, v2, v5
	v_mov_b32_e32 v2, v0
	s_nop 1
	v_permlane32_swap_b32_e32 v0, v2
	v_max_f32_e32 v2, v0, v2
	v_sub_f32_e32 v0, v2, v238
	v_cmp_ge_f32_e32 vcc, s93, v0
	s_cmp_eq_u64 vcc, exec
	v_mov_b32_e32 v0, 1.0
	s_cbranch_scc0 .LBB0_670

; #define SBAR() __builtin_amdgcn_sched_barrier(0)
; #define QK_WAIT(N) do { asm volatile("s_waitcnt lgkmcnt(" #N ")" ::: "memory"); SBAR(); } while (0)
; __device__ __forceinline__ float qkt_deep(f32x16& p0, f32x16& p1, const int (&ka)[4], const bf16x8 (&qr)[8]) {
;     ...
;   QD_RD0(0); QD_RD0(1); QD_RD0(2); QD_RD0(3); QD_RD0(4); QD_RD0(5); QD_RD0(6); QD_RD0(7);
;   QK_WAIT(7); QD_MM0(0); SBAR(); QD_RD1(0);
;   QK_WAIT(7); QD_MM0(1); SBAR(); QD_RD1(1);
;   QK_WAIT(7); QD_MM0(2); SBAR(); QD_RD1(2);
;   QK_WAIT(7); QD_MM0(3); SBAR(); QD_RD1(3);
;   QK_WAIT(7); QD_MM0(4); SBAR(); QD_RD1(4);
;   QK_WAIT(7); QD_MM0(5); SBAR(); QD_RD1(5);
;   QK_WAIT(7); QD_MM0(6); SBAR(); QD_RD1(6);
;   QK_WAIT(7); QD_MM0(7); SBAR(); QD_RD1(7);
;   QK_WAIT(7); QD_MM1(0); pm = fmaxf(p0[0], p0[1]); SBAR();
;   QK_WAIT(6); QD_MM1(1); pm = fmaxf(fmaxf(pm, p0[2]), p0[3]); SBAR();
;   QK_WAIT(5); QD_MM1(2); pm = fmaxf(fmaxf(pm, p0[4]), p0[5]); SBAR();
;   QK_WAIT(4); QD_MM1(3); pm = fmaxf(fmaxf(pm, p0[6]), p0[7]); SBAR();
;   QK_WAIT(3); QD_MM1(4); pm = fmaxf(fmaxf(pm, p0[8]), p0[9]); SBAR();
;   QK_WAIT(2); QD_MM1(5); pm = fmaxf(fmaxf(pm, p0[10]), p0[11]); SBAR();
;   QK_WAIT(1); QD_MM1(6); pm = fmaxf(fmaxf(pm, p0[12]), p0[13]); SBAR();
;   QK_WAIT(0); QD_MM1(7); pm = fmaxf(fmaxf(pm, p0[14]), p0[15]);
;   return pm;
; }
; template <int LD>
; __device__ __forceinline__ void attn256_body(const bf16_t* __restrict__ Qb, const bf16_t* __restrict__ Kh, const unsigned char* __restrict__ Vimg, int seq, char* lds, LAS unsigned char* ldsl,
;                                              f32x16 (&o)[8], float (&rli)[16]) {
;     ...
;   for (int j = 0; j < NT; ++j) {
;     const int cur = j & 1;
;     if (j + 1 < NT) { if (cur) A2_DMA(0, (j + 1) * 64); else A2_DMA(1, (j + 1) * 64); }
;     f32x16 p0 = f32x16{}, p1 = f32x16{}; float pmax;
;     { int ka[4];
; #pragma unroll
;       for (int q = 0; q < 4; ++q) ka[q] = kbase + cur * A2_STAGE + (((2 * q + hi) ^ (r32 & 7)) << 4);
;       pmax = qkt_deep(p0, p1, ka, qr); }
; #pragma unroll
;     for (int r = 0; r < 16; ++r) pmax = fmaxf(pmax, p1[r]);
;     pmax = half_swap_max(pmax);
;     float mn, alpha;
;     if (__builtin_expect(__all(pmax - m_reg <= ATT_THR / ATT_SCALE), 1)) { mn = m_reg; alpha = 1.f; }
;     else { mn = fmaxf(m_reg, pmax); alpha = __builtin_amdgcn_exp2f((m_reg - mn) * C); m_reg = mn; }
;     const float mnC = -mn * C; float ps;
.LBB0_677:
	s_setprio 1
	s_mul_i32 s4, s4, 0xc000
	s_waitcnt lgkmcnt(0)
	v_add_u32_e32 v0, s4, v221
	v_add_u32_e32 v248, v0, v233
	v_add_u32_e32 v249, v0, v234
	v_add_u32_e32 v250, v0, v235
	v_add_u32_e32 v0, v0, v236
	ds_read_b128 v[130:133], v248 offset:0
	ds_read_b128 v[134:137], v249 offset:0
	ds_read_b128 v[138:141], v250 offset:0
	ds_read_b128 v[142:145], v0 offset:0
	ds_read_b128 v[194:197], v248 offset:0x80
	ds_read_b128 v[198:201], v249 offset:0x80
	ds_read_b128 v[202:205], v250 offset:0x80
	ds_read_b128 v[206:209], v0 offset:0x80
	s_waitcnt lgkmcnt(7)
	s_nop 0
	v_mfma_f32_32x32x16_bf16 v[146:161], v[130:133], v[162:165], 0
	ds_read_b128 v[130:133], v248 offset:0x2000
	s_waitcnt lgkmcnt(7)
	s_nop 0
	v_mfma_f32_32x32x16_bf16 v[146:161], v[134:137], v[166:169], v[146:161]
	ds_read_b128 v[212:215], v249 offset:0x2000
	s_waitcnt lgkmcnt(7)
	s_nop 0
	v_mfma_f32_32x32x16_bf16 v[146:161], v[138:141], v[170:173], v[146:161]
	ds_read_b128 v[240:243], v250 offset:0x2000
	s_waitcnt lgkmcnt(7)
	s_nop 0
	v_mfma_f32_32x32x16_bf16 v[146:161], v[142:145], v[174:177], v[146:161]
	ds_read_b128 v[244:247], v0 offset:0x2000
	s_waitcnt lgkmcnt(7)
	s_nop 0
	v_mfma_f32_32x32x16_bf16 v[146:161], v[194:197], v[178:181], v[146:161]
	ds_read_b128 v[194:197], v248 offset:0x2080
	s_waitcnt lgkmcnt(7)
	s_nop 0
	v_mfma_f32_32x32x16_bf16 v[146:161], v[198:201], v[182:185], v[146:161]
	ds_read_b128 v[198:201], v249 offset:0x2080
	s_waitcnt lgkmcnt(7)
	s_nop 0
	v_mfma_f32_32x32x16_bf16 v[146:161], v[202:205], v[186:189], v[146:161]
	ds_read_b128 v[202:205], v250 offset:0x2080
	s_waitcnt lgkmcnt(7)
	s_nop 0
	v_mfma_f32_32x32x16_bf16 v[146:161], v[206:209], v[190:193], v[146:161]
	ds_read_b128 v[206:209], v0 offset:0x2080
	s_waitcnt lgkmcnt(7)
	s_nop 11
	v_max_f32_e32 v0, v147, v147
	v_max_f32_e32 v248, v146, v146
	v_mfma_f32_32x32x16_bf16 v[130:145], v[130:133], v[162:165], 0
	v_max_f32_e32 v0, v248, v0
	s_waitcnt lgkmcnt(6)
	s_nop 0
	v_mfma_f32_32x32x16_bf16 v[130:145], v[212:215], v[166:169], v[130:145]
	v_max3_f32 v0, v0, v148, v149
	s_waitcnt lgkmcnt(5)
	s_nop 0
	v_mfma_f32_32x32x16_bf16 v[130:145], v[240:243], v[170:173], v[130:145]
	v_max3_f32 v0, v0, v150, v151
	s_waitcnt lgkmcnt(4)
	s_nop 0
	v_mfma_f32_32x32x16_bf16 v[130:145], v[244:247], v[174:177], v[130:145]
	v_max3_f32 v0, v0, v152, v153
	s_waitcnt lgkmcnt(3)
	s_nop 0
	v_mfma_f32_32x32x16_bf16 v[130:145], v[194:197], v[178:181], v[130:145]
	v_max3_f32 v0, v0, v154, v155
	s_waitcnt lgkmcnt(2)
	s_nop 0
	v_mfma_f32_32x32x16_bf16 v[130:145], v[198:201], v[182:185], v[130:145]
	v_max3_f32 v0, v0, v156, v157
	s_waitcnt lgkmcnt(1)
	s_nop 0
	v_mfma_f32_32x32x16_bf16 v[130:145], v[202:205], v[186:189], v[130:145]
	v_max3_f32 v0, v0, v158, v159
	s_waitcnt lgkmcnt(0)
	s_nop 0
	v_mfma_f32_32x32x16_bf16 v[130:145], v[206:209], v[190:193], v[130:145]
	s_setprio 0
	v_max3_f32 v0, v0, v160, v161
	v_mul_f32_e32 v248, 0xbe0293ee, v238
	s_nop 9
	v_max3_f32 v194, v130, v131, v132
	v_max3_f32 v195, v133, v134, v135
	v_max3_f32 v196, v136, v137, v138
	v_max3_f32 v197, v139, v140, v141
	v_max3_f32 v198, v142, v143, v144
	v_max3_f32 v194, v194, v195, v196
	v_max3_f32 v197, v197, v198, v145
	v_max3_f32 v0, v0, v194, v197
	v_mov_b32_e32 v194, v0
	s_nop 1
	v_permlane32_swap_b32_e32 v0, v194
	v_max_f32_e32 v194, v0, v194
	v_sub_f32_e32 v0, v194, v238
	v_cmp_ge_f32_e32 vcc, s93, v0
	s_cmp_eq_u64 vcc, exec
	v_mov_b32_e32 v0, 1.0
	s_cbranch_scc0 .LBB0_684
